# RG-LRU output stores: uniform base in s[100:101], lane part folded into the 32-bit row offsets, stores use saddr+voffset form; 130 64-bit VALU adds removed per unit pair
# speedup vs baseline: 1.0067x; 1.0008x over previous
.LBB0_270:
	v_cndmask_b32_e64 v0, 1.0, v35, s[4:5]
	v_cndmask_b32_e64 v35, 0, v37, s[4:5]
	v_fmac_f32_e32 v35, v0, v1
	v_mul_f32_e32 v0, v0, v8
	v_cndmask_b32_e64 v37, v38, v41, s[4:5]
	v_cndmask_b32_e64 v36, v36, v40, s[4:5]
	v_fmac_f32_e32 v36, v37, v1
	v_mul_f32_e32 v37, v37, v8
	v_cndmask_b32_e64 v40, v46, v88, s[4:5]
	v_cndmask_b32_e64 v41, v43, v47, s[4:5]
	v_fmac_f32_e32 v41, v40, v1
	v_mul_f32_e32 v40, v40, v8
	s_ashr_i32 s13, s12, 31
	v_lshlrev_b32_e32 v88, 2, v93
	v_fmac_f32_e32 v25, v32, v41
	v_mul_f32_e32 v32, v32, v40
	v_fmac_f32_e32 v9, v34, v36
	v_mul_f32_e32 v34, v34, v37
	v_fmac_f32_e32 v10, v31, v36
	v_mul_f32_e32 v31, v31, v37
	v_fmac_f32_e32 v5, v28, v36
	v_mul_f32_e32 v28, v28, v37
	v_fmac_f32_e32 v11, v18, v36
	v_mul_f32_e32 v18, v18, v37
	v_fmac_f32_e32 v6, v12, v35
	v_mul_f32_e32 v36, v0, v12
	v_fmac_f32_e32 v4, v13, v35
	v_mul_f32_e32 v37, v0, v13
	s_lshl_b64 s[6:7], s[12:13], 12
	s_add_u32 s100, s24, s6
	s_addc_u32 s101, s25, s7
	v_fmac_f32_e32 v23, v29, v41
	v_mul_f32_e32 v29, v29, v40
	v_fmac_f32_e32 v21, v26, v41
	v_mul_f32_e32 v26, v26, v40
	v_fmac_f32_e32 v3, v16, v41
	v_mul_f32_e32 v40, v16, v40
	v_lshlrev_b32_e32 v12, 14, v92
	v_or_b32_e32 v12, v12, v88
	v_cvt_pk_bf16_f32 v16, v25, v32
	v_mov_b32_e32 v13, v89
	v_cndmask_b32_e64 v38, v42, v45, s[4:5]
	v_cndmask_b32_e64 v39, v39, v44, s[4:5]
	v_fmac_f32_e32 v39, v38, v1
	v_mul_f32_e32 v38, v38, v8
	v_mov_b32_e32 v96, v12
	v_or_b32_e32 v88, 0x1000, v12
	v_fmac_f32_e32 v22, v33, v39
	v_mul_f32_e32 v33, v33, v38
	v_fmac_f32_e32 v20, v30, v39
	v_mul_f32_e32 v30, v30, v38
	v_fmac_f32_e32 v19, v27, v39
	v_mul_f32_e32 v27, v27, v38
	v_fmac_f32_e32 v7, v17, v39
	v_mul_f32_e32 v38, v17, v38
	v_lshl_or_b32 v175, v138, 2, v133
	global_load_dword v172, v175, s[42:43]
	global_load_dword v173, v175, s[36:37]
	global_load_dword v174, v175, s[40:41]
	global_store_dword v96, v16, s[100:101] nt
	v_cvt_pk_bf16_f32 v13, v23, v29
	global_store_dword v88, v13, s[100:101] nt
	v_or_b32_e32 v98, 0x2000, v12
	v_mov_b32_e32 v99, v89
	v_cvt_pk_bf16_f32 v13, v21, v26
	v_or_b32_e32 v100, 0x3000, v12
	v_mov_b32_e32 v101, v89
	global_store_dword v98, v13, s[100:101] nt
	v_cvt_pk_bf16_f32 v3, v3, v40
	global_store_dword v100, v3, s[100:101] nt
	v_or_b32_e32 v102, 0x8000, v12
	v_mov_b32_e32 v103, v89
	v_cvt_pk_bf16_f32 v3, v22, v33
	global_store_dword v102, v3, s[100:101] nt
	v_or_b32_e32 v104, 0x9000, v12
	v_mov_b32_e32 v105, v89
	v_cvt_pk_bf16_f32 v3, v20, v30
	global_store_dword v104, v3, s[100:101] nt
	v_or_b32_e32 v106, 0xa000, v12
	v_mov_b32_e32 v107, v89
	v_cvt_pk_bf16_f32 v3, v19, v27
	global_store_dword v106, v3, s[100:101] nt
	v_or_b32_e32 v108, 0xb000, v12
	v_mov_b32_e32 v109, v89
	v_cvt_pk_bf16_f32 v3, v7, v38
	global_store_dword v108, v3, s[100:101] nt
	v_or_b32_e32 v110, 0x10000, v12
	v_mov_b32_e32 v111, v89
	v_cvt_pk_bf16_f32 v3, v9, v34
	global_store_dword v110, v3, s[100:101] nt
	v_or_b32_e32 v112, 0x11000, v12
	v_mov_b32_e32 v113, v89
	v_cvt_pk_bf16_f32 v3, v10, v31
	global_store_dword v112, v3, s[100:101] nt
	v_or_b32_e32 v114, 0x12000, v12
	v_mov_b32_e32 v115, v89
	v_cvt_pk_bf16_f32 v3, v5, v28
	global_store_dword v114, v3, s[100:101] nt
	v_or_b32_e32 v116, 0x13000, v12
	v_mov_b32_e32 v117, v89
	v_cvt_pk_bf16_f32 v3, v11, v18
	global_store_dword v116, v3, s[100:101] nt
	v_or_b32_e32 v118, 0x18000, v12
	v_mov_b32_e32 v119, v89
	v_cvt_pk_bf16_f32 v3, v6, v36
	global_store_dword v118, v3, s[100:101] nt
	v_or_b32_e32 v120, 0x19000, v12
	v_mov_b32_e32 v121, v89
	v_fmac_f32_e32 v2, v14, v35
	v_mul_f32_e32 v14, v0, v14
	v_cvt_pk_bf16_f32 v3, v4, v37
	v_fmac_f32_e32 v15, v24, v35
	v_mul_f32_e32 v0, v0, v24
	s_lshl_b32 s8, s65, 11
	global_store_dword v120, v3, s[100:101] nt
	v_or_b32_e32 v122, 0x1a000, v12
	v_mov_b32_e32 v123, v89
	s_or_b32 s8, s8, s76
	v_cvt_pk_bf16_f32 v4, v2, v14
	v_or_b32_e32 v124, 0x1b000, v12
	v_mov_b32_e32 v125, v89
	v_cmp_gt_i32_e64 s[6:7], 32, v90
	v_add_u32_e32 v92, s8, v90
	global_store_dword v122, v4, s[100:101] nt
	v_cvt_pk_bf16_f32 v2, v15, v0
	v_lshl_add_u32 v90, v90, 3, 16
	global_store_dword v124, v2, s[100:101] nt
	s_and_saveexec_b64 s[8:9], s[6:7]
	s_cbranch_execz .LBB0_272
	ds_read2_b64 v[0:3], v90 offset0:192 offset1:224
	ds_read2_b64 v[4:7], v90 offset0:128 offset1:160
	ds_read2_b64 v[8:11], v90 offset0:64 offset1:96
	ds_read2_b64 v[12:15], v90 offset1:32
	v_ashrrev_i32_e32 v93, 31, v92
	s_waitcnt lgkmcnt(3)
	v_fma_f32 v16, 0, v2, v3
	v_pk_mul_f32 v[2:3], v[2:3], v[0:1]
	v_fma_f32 v0, v0, v16, v1
	s_waitcnt lgkmcnt(2)
	v_fma_f32 v0, v6, v0, v7
	v_fma_f32 v0, v4, v0, v5
	s_waitcnt lgkmcnt(1)
	v_fma_f32 v1, v10, v0, v11
	v_mov_b32_e32 v0, v2
	v_mov_b32_e32 v16, v6
	v_mov_b32_e32 v17, v8
	v_pk_mul_f32 v[2:3], v[2:3], v[6:7]
	v_pk_fma_f32 v[0:1], v[0:1], v[16:17], v[8:9]
	v_pk_mul_f32 v[2:3], v[2:3], v[4:5]
	s_waitcnt lgkmcnt(0)
	v_mov_b32_e32 v11, v14
	v_mov_b32_e32 v3, v1
	v_pk_mul_f32 v[0:1], v[2:3], v[10:11]
	v_pk_fma_f32 v[2:3], v[2:3], v[10:11], v[14:15]
	v_pk_mul_f32 v[0:1], v[0:1], v[8:9]
	v_mov_b32_e32 v4, v14
	v_mov_b32_e32 v2, v0
	v_mov_b32_e32 v5, v12
	v_pk_mul_f32 v[0:1], v[0:1], v[14:15]
	v_pk_fma_f32 v[2:3], v[2:3], v[4:5], v[12:13]
	v_pk_mul_f32 v[0:1], v[0:1], v[12:13]
	s_nop 0
	v_mov_b32_e32 v1, v3
	v_lshl_add_u64 v[2:3], v[92:93], 3, s[30:31]
	global_store_dwordx2 v[2:3], v[0:1], off

.LBB0_278:
	v_cndmask_b32_e64 v0, 1.0, v35, s[4:5]
	v_cndmask_b32_e64 v35, 0, v37, s[4:5]
	v_fmac_f32_e32 v35, v0, v1
	v_mul_f32_e32 v0, v0, v8
	v_cndmask_b32_e64 v37, v38, v41, s[4:5]
	v_cndmask_b32_e64 v36, v36, v40, s[4:5]
	v_fmac_f32_e32 v36, v37, v1
	v_mul_f32_e32 v37, v37, v8
	v_cndmask_b32_e64 v40, v46, v93, s[4:5]
	v_cndmask_b32_e64 v41, v43, v47, s[4:5]
	v_fmac_f32_e32 v41, v40, v1
	v_mul_f32_e32 v40, v40, v8
	v_fmac_f32_e32 v25, v32, v41
	v_mul_f32_e32 v32, v32, v40
	v_fmac_f32_e32 v23, v29, v41
	v_mul_f32_e32 v29, v29, v40
	v_fmac_f32_e32 v20, v26, v41
	v_mul_f32_e32 v26, v26, v40
	v_fmac_f32_e32 v3, v16, v41
	v_mul_f32_e32 v40, v16, v40
	v_cvt_pk_bf16_f32 v16, v25, v32
	v_cndmask_b32_e64 v38, v42, v45, s[4:5]
	v_cndmask_b32_e64 v39, v39, v44, s[4:5]
	v_fmac_f32_e32 v39, v38, v1
	v_mul_f32_e32 v38, v38, v8
	v_fmac_f32_e32 v10, v34, v36
	v_mul_f32_e32 v34, v34, v37
	v_fmac_f32_e32 v6, v31, v36
	v_mul_f32_e32 v31, v31, v37
	v_fmac_f32_e32 v4, v28, v36
	v_mul_f32_e32 v28, v28, v37
	v_fmac_f32_e32 v11, v18, v36
	v_mul_f32_e32 v18, v18, v37
	v_fmac_f32_e32 v9, v12, v35
	v_mul_f32_e32 v36, v0, v12
	v_fmac_f32_e32 v5, v13, v35
	v_mul_f32_e32 v37, v0, v13
	v_lshl_or_b32 v175, v138, 2, v134
	global_load_dword v172, v175, s[42:43]
	global_load_dword v173, v175, s[36:37]
	global_load_dword v174, v175, s[40:41]
	global_store_dword v96, v16, s[100:101] offset:128 nt
	v_fmac_f32_e32 v24, v33, v39
	v_mul_f32_e32 v33, v33, v38
	v_fmac_f32_e32 v21, v30, v39
	v_mul_f32_e32 v30, v30, v38
	v_fmac_f32_e32 v19, v27, v39
	v_mul_f32_e32 v27, v27, v38
	v_fmac_f32_e32 v7, v17, v39
	v_mul_f32_e32 v38, v17, v38
	v_fmac_f32_e32 v2, v14, v35
	v_mul_f32_e32 v14, v0, v14
	v_fmac_f32_e32 v15, v22, v35
	v_mul_f32_e32 v0, v0, v22
	v_cvt_pk_bf16_f32 v22, v23, v29
	global_store_dword v88, v22, s[100:101] offset:128 nt
	v_cvt_pk_bf16_f32 v20, v20, v26
	global_store_dword v98, v20, s[100:101] offset:128 nt
	v_cvt_pk_bf16_f32 v3, v3, v40
	global_store_dword v100, v3, s[100:101] offset:128 nt
	v_cvt_pk_bf16_f32 v3, v24, v33
	global_store_dword v102, v3, s[100:101] offset:128 nt
	v_cvt_pk_bf16_f32 v3, v21, v30
	global_store_dword v104, v3, s[100:101] offset:128 nt
	v_cvt_pk_bf16_f32 v3, v19, v27
	global_store_dword v106, v3, s[100:101] offset:128 nt
	v_cvt_pk_bf16_f32 v3, v7, v38
	global_store_dword v108, v3, s[100:101] offset:128 nt
	v_cvt_pk_bf16_f32 v3, v10, v34
	global_store_dword v110, v3, s[100:101] offset:128 nt
	v_cvt_pk_bf16_f32 v3, v6, v31
	global_store_dword v112, v3, s[100:101] offset:128 nt
	v_cvt_pk_bf16_f32 v3, v4, v28
	global_store_dword v114, v3, s[100:101] offset:128 nt
	v_cvt_pk_bf16_f32 v3, v11, v18
	global_store_dword v116, v3, s[100:101] offset:128 nt
	v_cvt_pk_bf16_f32 v3, v9, v36
	global_store_dword v118, v3, s[100:101] offset:128 nt
	v_cvt_pk_bf16_f32 v3, v5, v37
	global_store_dword v120, v3, s[100:101] offset:128 nt
	v_cvt_pk_bf16_f32 v4, v2, v14
	global_store_dword v122, v4, s[100:101] offset:128 nt
	v_cvt_pk_bf16_f32 v2, v15, v0
	global_store_dword v124, v2, s[100:101] offset:128 nt
	s_and_saveexec_b64 s[12:13], s[6:7]
	s_cbranch_execz .LBB0_280
	v_add_u32_e32 v12, 0x800, v90
	ds_read2_b64 v[0:3], v12 offset0:192 offset1:224
	ds_read2_b64 v[4:7], v12 offset0:128 offset1:160
	ds_read2_b64 v[8:11], v12 offset0:64 offset1:96
	ds_read2_b64 v[12:15], v12 offset1:32
	s_waitcnt lgkmcnt(3)
	v_fma_f32 v16, 0, v2, v3
	v_pk_mul_f32 v[2:3], v[2:3], v[0:1]
	v_fma_f32 v0, v0, v16, v1
	s_waitcnt lgkmcnt(2)
	v_fma_f32 v0, v6, v0, v7
	v_fma_f32 v0, v4, v0, v5
	s_waitcnt lgkmcnt(1)
	v_fma_f32 v1, v10, v0, v11
	v_mov_b32_e32 v0, v2
	v_mov_b32_e32 v16, v6
	v_mov_b32_e32 v17, v8
	v_pk_mul_f32 v[2:3], v[2:3], v[6:7]
	v_pk_fma_f32 v[0:1], v[0:1], v[16:17], v[8:9]
	v_pk_mul_f32 v[2:3], v[2:3], v[4:5]
	s_waitcnt lgkmcnt(0)
	v_mov_b32_e32 v11, v14
	v_mov_b32_e32 v3, v1
	v_pk_mul_f32 v[0:1], v[2:3], v[10:11]
	v_pk_fma_f32 v[2:3], v[2:3], v[10:11], v[14:15]
	v_pk_mul_f32 v[0:1], v[0:1], v[8:9]
	v_mov_b32_e32 v4, v14
	v_mov_b32_e32 v2, v0
	v_mov_b32_e32 v5, v12
	v_pk_mul_f32 v[0:1], v[0:1], v[14:15]
	v_pk_fma_f32 v[2:3], v[2:3], v[4:5], v[12:13]
	v_pk_mul_f32 v[0:1], v[0:1], v[12:13]
	v_add_u32_e32 v2, 32, v92
	v_mov_b32_e32 v1, v3
	v_ashrrev_i32_e32 v3, 31, v2
	v_lshl_add_u64 v[2:3], v[2:3], 3, s[30:31]
	global_store_dwordx2 v[2:3], v[0:1], off

.LBB0_286:
	v_cndmask_b32_e64 v0, 1.0, v35, s[4:5]
	v_cndmask_b32_e64 v35, 0, v37, s[4:5]
	v_fmac_f32_e32 v35, v0, v1
	v_mul_f32_e32 v0, v0, v8
	v_cndmask_b32_e64 v37, v38, v41, s[4:5]
	v_cndmask_b32_e64 v36, v36, v40, s[4:5]
	v_fmac_f32_e32 v36, v37, v1
	v_mul_f32_e32 v37, v37, v8
	v_cndmask_b32_e64 v40, v46, v93, s[4:5]
	v_cndmask_b32_e64 v41, v43, v47, s[4:5]
	v_fmac_f32_e32 v41, v40, v1
	v_mul_f32_e32 v40, v40, v8
	v_fmac_f32_e32 v25, v32, v41
	v_mul_f32_e32 v32, v32, v40
	v_fmac_f32_e32 v23, v29, v41
	v_mul_f32_e32 v29, v29, v40
	v_fmac_f32_e32 v20, v26, v41
	v_mul_f32_e32 v26, v26, v40
	v_fmac_f32_e32 v3, v16, v41
	v_mul_f32_e32 v40, v16, v40
	v_cvt_pk_bf16_f32 v16, v25, v32
	v_cndmask_b32_e64 v38, v42, v45, s[4:5]
	v_cndmask_b32_e64 v39, v39, v44, s[4:5]
	v_fmac_f32_e32 v39, v38, v1
	v_mul_f32_e32 v38, v38, v8
	v_fmac_f32_e32 v10, v34, v36
	v_mul_f32_e32 v34, v34, v37
	v_fmac_f32_e32 v6, v31, v36
	v_mul_f32_e32 v31, v31, v37
	v_fmac_f32_e32 v4, v28, v36
	v_mul_f32_e32 v28, v28, v37
	v_fmac_f32_e32 v11, v18, v36
	v_mul_f32_e32 v18, v18, v37
	v_fmac_f32_e32 v9, v12, v35
	v_mul_f32_e32 v36, v0, v12
	v_fmac_f32_e32 v5, v13, v35
	v_mul_f32_e32 v37, v0, v13
	v_lshl_or_b32 v175, v138, 2, v135
	global_load_dword v172, v175, s[42:43]
	global_load_dword v173, v175, s[36:37]
	global_load_dword v174, v175, s[40:41]
	global_store_dword v96, v16, s[100:101] offset:256 nt
	v_fmac_f32_e32 v24, v33, v39
	v_mul_f32_e32 v33, v33, v38
	v_fmac_f32_e32 v21, v30, v39
	v_mul_f32_e32 v30, v30, v38
	v_fmac_f32_e32 v19, v27, v39
	v_mul_f32_e32 v27, v27, v38
	v_fmac_f32_e32 v7, v17, v39
	v_mul_f32_e32 v38, v17, v38
	v_fmac_f32_e32 v2, v14, v35
	v_mul_f32_e32 v14, v0, v14
	v_fmac_f32_e32 v15, v22, v35
	v_mul_f32_e32 v0, v0, v22
	v_cvt_pk_bf16_f32 v22, v23, v29
	global_store_dword v88, v22, s[100:101] offset:256 nt
	v_cvt_pk_bf16_f32 v20, v20, v26
	global_store_dword v98, v20, s[100:101] offset:256 nt
	v_cvt_pk_bf16_f32 v3, v3, v40
	global_store_dword v100, v3, s[100:101] offset:256 nt
	v_cvt_pk_bf16_f32 v3, v24, v33
	global_store_dword v102, v3, s[100:101] offset:256 nt
	v_cvt_pk_bf16_f32 v3, v21, v30
	global_store_dword v104, v3, s[100:101] offset:256 nt
	v_cvt_pk_bf16_f32 v3, v19, v27
	global_store_dword v106, v3, s[100:101] offset:256 nt
	v_cvt_pk_bf16_f32 v3, v7, v38
	global_store_dword v108, v3, s[100:101] offset:256 nt
	v_cvt_pk_bf16_f32 v3, v10, v34
	global_store_dword v110, v3, s[100:101] offset:256 nt
	v_cvt_pk_bf16_f32 v3, v6, v31
	global_store_dword v112, v3, s[100:101] offset:256 nt
	v_cvt_pk_bf16_f32 v3, v4, v28
	global_store_dword v114, v3, s[100:101] offset:256 nt
	v_cvt_pk_bf16_f32 v3, v11, v18
	global_store_dword v116, v3, s[100:101] offset:256 nt
	v_cvt_pk_bf16_f32 v3, v9, v36
	global_store_dword v118, v3, s[100:101] offset:256 nt
	v_cvt_pk_bf16_f32 v3, v5, v37
	global_store_dword v120, v3, s[100:101] offset:256 nt
	v_cvt_pk_bf16_f32 v4, v2, v14
	global_store_dword v122, v4, s[100:101] offset:256 nt
	v_cvt_pk_bf16_f32 v2, v15, v0
	global_store_dword v124, v2, s[100:101] offset:256 nt
	s_and_saveexec_b64 s[12:13], s[6:7]
	s_cbranch_execz .LBB0_288
	v_add_u32_e32 v12, 0x1000, v90
	ds_read2_b64 v[0:3], v12 offset0:192 offset1:224
	ds_read2_b64 v[4:7], v12 offset0:128 offset1:160
	ds_read2_b64 v[8:11], v12 offset0:64 offset1:96
	ds_read2_b64 v[12:15], v12 offset1:32
	s_waitcnt lgkmcnt(3)
	v_fma_f32 v16, 0, v2, v3
	v_pk_mul_f32 v[2:3], v[2:3], v[0:1]
	v_fma_f32 v0, v0, v16, v1
	s_waitcnt lgkmcnt(2)
	v_fma_f32 v0, v6, v0, v7
	v_fma_f32 v0, v4, v0, v5
	s_waitcnt lgkmcnt(1)
	v_fma_f32 v1, v10, v0, v11
	v_mov_b32_e32 v0, v2
	v_mov_b32_e32 v16, v6
	v_mov_b32_e32 v17, v8
	v_pk_mul_f32 v[2:3], v[2:3], v[6:7]
	v_pk_fma_f32 v[0:1], v[0:1], v[16:17], v[8:9]
	v_pk_mul_f32 v[2:3], v[2:3], v[4:5]
	s_waitcnt lgkmcnt(0)
	v_mov_b32_e32 v11, v14
	v_mov_b32_e32 v3, v1
	v_pk_mul_f32 v[0:1], v[2:3], v[10:11]
	v_pk_fma_f32 v[2:3], v[2:3], v[10:11], v[14:15]
	v_pk_mul_f32 v[0:1], v[0:1], v[8:9]
	v_mov_b32_e32 v4, v14
	v_mov_b32_e32 v2, v0
	v_mov_b32_e32 v5, v12
	v_pk_mul_f32 v[0:1], v[0:1], v[14:15]
	v_pk_fma_f32 v[2:3], v[2:3], v[4:5], v[12:13]
	v_pk_mul_f32 v[0:1], v[0:1], v[12:13]
	v_add_u32_e32 v2, 64, v92
	v_mov_b32_e32 v1, v3
	v_ashrrev_i32_e32 v3, 31, v2
	v_lshl_add_u64 v[2:3], v[2:3], 3, s[30:31]
	global_store_dwordx2 v[2:3], v[0:1], off

.LBB0_294:
	v_cndmask_b32_e64 v0, 1.0, v35, s[4:5]
	v_cndmask_b32_e64 v35, 0, v37, s[4:5]
	v_fmac_f32_e32 v35, v0, v1
	v_mul_f32_e32 v0, v0, v8
	v_cndmask_b32_e64 v37, v38, v41, s[4:5]
	v_cndmask_b32_e64 v36, v36, v40, s[4:5]
	v_fmac_f32_e32 v36, v37, v1
	v_mul_f32_e32 v37, v37, v8
	v_cndmask_b32_e64 v40, v46, v48, s[4:5]
	v_cndmask_b32_e64 v41, v43, v47, s[4:5]
	v_fmac_f32_e32 v41, v40, v1
	v_mul_f32_e32 v40, v40, v8
	v_fmac_f32_e32 v25, v32, v41
	v_mul_f32_e32 v32, v32, v40
	v_fmac_f32_e32 v23, v29, v41
	v_mul_f32_e32 v29, v29, v40
	v_fmac_f32_e32 v20, v26, v41
	v_mul_f32_e32 v26, v26, v40
	v_fmac_f32_e32 v3, v16, v41
	v_mul_f32_e32 v40, v16, v40
	v_cvt_pk_bf16_f32 v16, v25, v32
	v_cndmask_b32_e64 v38, v42, v45, s[4:5]
	v_cndmask_b32_e64 v39, v39, v44, s[4:5]
	v_fmac_f32_e32 v39, v38, v1
	v_mul_f32_e32 v38, v38, v8
	v_fmac_f32_e32 v10, v34, v36
	v_mul_f32_e32 v34, v34, v37
	v_fmac_f32_e32 v6, v31, v36
	v_mul_f32_e32 v31, v31, v37
	v_fmac_f32_e32 v4, v28, v36
	v_mul_f32_e32 v28, v28, v37
	v_fmac_f32_e32 v11, v18, v36
	v_mul_f32_e32 v18, v18, v37
	v_fmac_f32_e32 v9, v12, v35
	v_mul_f32_e32 v36, v0, v12
	v_fmac_f32_e32 v5, v13, v35
	v_mul_f32_e32 v37, v0, v13
	global_store_dword v96, v16, s[100:101] offset:384 nt
	v_fmac_f32_e32 v24, v33, v39
	v_mul_f32_e32 v33, v33, v38
	v_fmac_f32_e32 v21, v30, v39
	v_mul_f32_e32 v30, v30, v38
	v_fmac_f32_e32 v19, v27, v39
	v_mul_f32_e32 v27, v27, v38
	v_fmac_f32_e32 v7, v17, v39
	v_mul_f32_e32 v38, v17, v38
	v_fmac_f32_e32 v2, v14, v35
	v_mul_f32_e32 v14, v0, v14
	v_fmac_f32_e32 v15, v22, v35
	v_mul_f32_e32 v0, v0, v22
	v_cvt_pk_bf16_f32 v22, v23, v29
	global_store_dword v88, v22, s[100:101] offset:384 nt
	v_cvt_pk_bf16_f32 v20, v20, v26
	global_store_dword v98, v20, s[100:101] offset:384 nt
	v_cvt_pk_bf16_f32 v3, v3, v40
	global_store_dword v100, v3, s[100:101] offset:384 nt
	v_cvt_pk_bf16_f32 v3, v24, v33
	global_store_dword v102, v3, s[100:101] offset:384 nt
	v_cvt_pk_bf16_f32 v3, v21, v30
	global_store_dword v104, v3, s[100:101] offset:384 nt
	v_cvt_pk_bf16_f32 v3, v19, v27
	global_store_dword v106, v3, s[100:101] offset:384 nt
	v_cvt_pk_bf16_f32 v3, v7, v38
	global_store_dword v108, v3, s[100:101] offset:384 nt
	v_cvt_pk_bf16_f32 v3, v10, v34
	global_store_dword v110, v3, s[100:101] offset:384 nt
	v_cvt_pk_bf16_f32 v3, v6, v31
	global_store_dword v112, v3, s[100:101] offset:384 nt
	v_cvt_pk_bf16_f32 v3, v4, v28
	global_store_dword v114, v3, s[100:101] offset:384 nt
	v_cvt_pk_bf16_f32 v3, v11, v18
	global_store_dword v116, v3, s[100:101] offset:384 nt
	v_cvt_pk_bf16_f32 v3, v9, v36
	global_store_dword v118, v3, s[100:101] offset:384 nt
	v_cvt_pk_bf16_f32 v3, v5, v37
	global_store_dword v120, v3, s[100:101] offset:384 nt
	v_cvt_pk_bf16_f32 v4, v2, v14
	global_store_dword v122, v4, s[100:101] offset:384 nt
	v_cvt_pk_bf16_f32 v2, v15, v0
	global_store_dword v124, v2, s[100:101] offset:384 nt
	s_and_saveexec_b64 s[4:5], s[6:7]
	s_cbranch_execz .LBB0_244
	v_add_u32_e32 v12, 0x1800, v90
	ds_read2_b64 v[0:3], v12 offset0:192 offset1:224
	ds_read2_b64 v[4:7], v12 offset0:128 offset1:160
	ds_read2_b64 v[8:11], v12 offset0:64 offset1:96
	ds_read2_b64 v[12:15], v12 offset1:32
	s_waitcnt lgkmcnt(3)
	v_fma_f32 v16, 0, v2, v3
	v_pk_mul_f32 v[2:3], v[2:3], v[0:1]
	v_fma_f32 v0, v0, v16, v1
	s_waitcnt lgkmcnt(2)
	v_fma_f32 v0, v6, v0, v7
	v_fma_f32 v0, v4, v0, v5
	s_waitcnt lgkmcnt(1)
	v_fma_f32 v1, v10, v0, v11
	v_mov_b32_e32 v0, v2
	v_mov_b32_e32 v16, v6
	v_mov_b32_e32 v17, v8
	v_pk_mul_f32 v[2:3], v[2:3], v[6:7]
	v_pk_fma_f32 v[0:1], v[0:1], v[16:17], v[8:9]
	v_pk_mul_f32 v[2:3], v[2:3], v[4:5]
	s_waitcnt lgkmcnt(0)
	v_mov_b32_e32 v11, v14
	v_mov_b32_e32 v3, v1
	v_pk_mul_f32 v[0:1], v[2:3], v[10:11]
	v_pk_fma_f32 v[2:3], v[2:3], v[10:11], v[14:15]
	v_pk_mul_f32 v[0:1], v[0:1], v[8:9]
	v_mov_b32_e32 v4, v14
	v_mov_b32_e32 v2, v0
	v_mov_b32_e32 v5, v12
	v_pk_mul_f32 v[0:1], v[0:1], v[14:15]
	v_pk_fma_f32 v[2:3], v[2:3], v[4:5], v[12:13]
	v_pk_mul_f32 v[0:1], v[0:1], v[12:13]
	v_add_u32_e32 v2, 0x60, v92
	v_mov_b32_e32 v1, v3
	v_ashrrev_i32_e32 v3, 31, v2
	v_lshl_add_u64 v[2:3], v[2:3], 3, s[30:31]
	global_store_dwordx2 v[2:3], v[0:1], off
	s_branch .LBB0_244

.LBB0_331:
	v_lshl_add_u64 v[126:127], s[36:37], 0, v[88:89]
	v_lshl_add_u64 v[128:129], s[40:41], 0, v[88:89]
	v_lshl_add_u64 v[130:131], s[42:43], 0, v[88:89]
	v_cndmask_b32_e64 v1, v13, 1.0, s[0:1]
	v_cndmask_b32_e64 v2, v10, 0, s[0:1]
	v_fmac_f32_e32 v2, v1, v3
	v_mul_f32_e32 v1, v1, v0
	v_cndmask_b32_e64 v10, v42, v15, s[0:1]
	v_cndmask_b32_e64 v13, v17, v14, s[0:1]
	v_fmac_f32_e32 v13, v10, v3
	v_mul_f32_e32 v10, v10, v0
	v_cndmask_b32_e64 v14, v46, v43, s[0:1]
	v_cndmask_b32_e64 v15, v44, v41, s[0:1]
	v_fmac_f32_e32 v15, v14, v3
	v_mul_f32_e32 v14, v14, v0
	s_ashr_i32 s9, s8, 31
	v_lshlrev_b32_e32 v88, 2, v94
	v_cndmask_b32_e64 v17, v96, v47, s[0:1]
	v_cndmask_b32_e64 v41, v91, v45, s[0:1]
	v_fmac_f32_e32 v41, v17, v3
	v_mul_f32_e32 v17, v17, v0
	v_fmac_f32_e32 v18, v32, v2
	v_mul_f32_e32 v32, v1, v32
	v_fmac_f32_e32 v31, v33, v2
	v_mul_f32_e32 v33, v1, v33
	v_fmac_f32_e32 v30, v34, v2
	v_mul_f32_e32 v34, v1, v34
	v_fmac_f32_e32 v29, v35, v2
	v_mul_f32_e32 v1, v1, v35
	v_fmac_f32_e32 v19, v20, v13
	v_mul_f32_e32 v2, v20, v10
	v_fmac_f32_e32 v28, v36, v13
	v_mul_f32_e32 v20, v36, v10
	v_fmac_f32_e32 v27, v37, v13
	v_mul_f32_e32 v35, v37, v10
	v_fmac_f32_e32 v26, v38, v13
	v_mul_f32_e32 v10, v38, v10
	v_fmac_f32_e32 v23, v12, v15
	v_mul_f32_e32 v38, v12, v14
	s_lshl_b64 s[4:5], s[8:9], 12
	s_add_u32 s100, s22, s4
	s_addc_u32 s101, s23, s5
	v_fmac_f32_e32 v24, v40, v15
	v_mul_f32_e32 v37, v40, v14
	v_fmac_f32_e32 v7, v4, v41
	v_mul_f32_e32 v40, v4, v17
	v_lshlrev_b32_e32 v12, 14, v93
	v_or_b32_e32 v12, v12, v88
	v_mov_b32_e32 v13, v89
	v_cvt_pk_bf16_f32 v4, v18, v32
	v_mov_b32_e32 v96, v12
	global_load_dword v172, v[130:131], off offset:128
	global_load_dword v173, v[126:127], off offset:128
	global_load_dword v174, v[128:129], off offset:128
	global_store_dword v96, v4, s[100:101] nt
	v_or_b32_e32 v88, 0x1000, v12
	v_fmac_f32_e32 v21, v22, v15
	v_mul_f32_e32 v22, v22, v14
	v_fmac_f32_e32 v25, v39, v15
	v_mul_f32_e32 v36, v39, v14
	v_cvt_pk_bf16_f32 v4, v31, v33
	v_or_b32_e32 v98, 0x2000, v12
	v_mov_b32_e32 v99, v89
	global_store_dword v88, v4, s[100:101] nt
	v_or_b32_e32 v100, 0x3000, v12
	v_mov_b32_e32 v101, v89
	v_cvt_pk_bf16_f32 v4, v30, v34
	global_store_dword v98, v4, s[100:101] nt
	v_cvt_pk_bf16_f32 v1, v29, v1
	global_store_dword v100, v1, s[100:101] nt
	v_or_b32_e32 v102, 0x8000, v12
	v_mov_b32_e32 v103, v89
	v_cvt_pk_bf16_f32 v1, v19, v2
	global_store_dword v102, v1, s[100:101] nt
	v_or_b32_e32 v104, 0x9000, v12
	v_mov_b32_e32 v105, v89
	v_cvt_pk_bf16_f32 v1, v28, v20
	global_store_dword v104, v1, s[100:101] nt
	v_or_b32_e32 v106, 0xa000, v12
	v_mov_b32_e32 v107, v89
	v_cvt_pk_bf16_f32 v1, v27, v35
	global_store_dword v106, v1, s[100:101] nt
	v_or_b32_e32 v108, 0xb000, v12
	v_mov_b32_e32 v109, v89
	v_cvt_pk_bf16_f32 v1, v26, v10
	global_store_dword v108, v1, s[100:101] nt
	v_or_b32_e32 v110, 0x10000, v12
	v_mov_b32_e32 v111, v89
	v_cvt_pk_bf16_f32 v1, v21, v22
	global_store_dword v110, v1, s[100:101] nt
	v_or_b32_e32 v112, 0x11000, v12
	v_mov_b32_e32 v113, v89
	v_cvt_pk_bf16_f32 v1, v25, v36
	global_store_dword v112, v1, s[100:101] nt
	v_or_b32_e32 v114, 0x12000, v12
	v_mov_b32_e32 v115, v89
	v_cvt_pk_bf16_f32 v1, v24, v37
	global_store_dword v114, v1, s[100:101] nt
	v_or_b32_e32 v116, 0x13000, v12
	v_mov_b32_e32 v117, v89
	v_fmac_f32_e32 v8, v16, v41
	v_mul_f32_e32 v16, v16, v17
	v_cvt_pk_bf16_f32 v1, v23, v38
	global_store_dword v116, v1, s[100:101] nt
	v_or_b32_e32 v118, 0x18000, v12
	v_mov_b32_e32 v119, v89
	v_fmac_f32_e32 v5, v9, v41
	v_mul_f32_e32 v39, v9, v17
	v_cvt_pk_bf16_f32 v1, v8, v16
	global_store_dword v118, v1, s[100:101] nt
	v_or_b32_e32 v120, 0x19000, v12
	v_mov_b32_e32 v121, v89
	v_cvt_pk_bf16_f32 v1, v5, v39
	v_fmac_f32_e32 v11, v6, v41
	v_mul_f32_e32 v6, v6, v17
	s_lshl_b32 s6, s63, 11
	global_store_dword v120, v1, s[100:101] nt
	v_or_b32_e32 v122, 0x1a000, v12
	v_mov_b32_e32 v123, v89
	s_or_b32 s6, s6, s70
	v_cvt_pk_bf16_f32 v1, v7, v40
	v_or_b32_e32 v124, 0x1b000, v12
	v_mov_b32_e32 v125, v89
	v_lshl_add_u32 v142, v92, 3, 16
	v_cmp_gt_i32_e64 s[4:5], 32, v92
	v_add_u32_e32 v92, s6, v92
	global_store_dword v122, v1, s[100:101] nt
	v_cvt_pk_bf16_f32 v2, v11, v6
	global_store_dword v124, v2, s[100:101] nt
	s_and_saveexec_b64 s[6:7], s[4:5]
	s_cbranch_execz .LBB0_333
	ds_read2_b64 v[0:3], v142 offset1:32
	ds_read2_b64 v[4:7], v142 offset0:64 offset1:96
	ds_read2_b64 v[8:11], v142 offset0:128 offset1:160
	ds_read2_b64 v[12:15], v142 offset0:192 offset1:224
	v_ashrrev_i32_e32 v93, 31, v92
	s_waitcnt lgkmcnt(3)
	v_fma_f32 v16, 0, v0, v1
	v_pk_mul_f32 v[0:1], v[0:1], v[2:3]
	v_fma_f32 v2, v2, v16, v3
	s_waitcnt lgkmcnt(2)
	v_fma_f32 v2, v4, v2, v5
	v_fma_f32 v2, v6, v2, v7
	s_waitcnt lgkmcnt(1)
	v_fma_f32 v3, v8, v2, v9
	v_mov_b32_e32 v2, v0
	v_mov_b32_e32 v16, v4
	v_mov_b32_e32 v17, v10
	v_pk_mul_f32 v[0:1], v[0:1], v[4:5]
	v_pk_fma_f32 v[2:3], v[2:3], v[16:17], v[10:11]
	v_pk_mul_f32 v[0:1], v[0:1], v[6:7]
	s_waitcnt lgkmcnt(0)
	v_mov_b32_e32 v9, v12
	v_mov_b32_e32 v1, v3
	v_pk_mul_f32 v[2:3], v[0:1], v[8:9]
	v_pk_fma_f32 v[0:1], v[0:1], v[8:9], v[12:13]
	v_pk_mul_f32 v[2:3], v[2:3], v[10:11]
	v_mov_b32_e32 v4, v12
	v_mov_b32_e32 v0, v2
	v_mov_b32_e32 v5, v14
	v_pk_mul_f32 v[2:3], v[2:3], v[12:13]
	v_pk_fma_f32 v[0:1], v[0:1], v[4:5], v[14:15]
	v_pk_mul_f32 v[2:3], v[2:3], v[14:15]
	s_nop 0
	v_mov_b32_e32 v3, v1
	v_lshl_add_u64 v[0:1], v[92:93], 3, s[24:25]
	global_store_dwordx2 v[0:1], v[2:3], off

.LBB0_344:
	v_cndmask_b32_e64 v1, v13, 1.0, s[0:1]
	v_cndmask_b32_e64 v2, v10, 0, s[0:1]
	v_fmac_f32_e32 v2, v1, v3
	v_mul_f32_e32 v1, v1, v0
	v_cndmask_b32_e64 v10, v42, v15, s[0:1]
	v_cndmask_b32_e64 v13, v17, v14, s[0:1]
	v_fmac_f32_e32 v13, v10, v3
	v_mul_f32_e32 v10, v10, v0
	v_cndmask_b32_e64 v14, v46, v43, s[0:1]
	v_cndmask_b32_e64 v15, v44, v41, s[0:1]
	v_fmac_f32_e32 v15, v14, v3
	v_mul_f32_e32 v14, v14, v0
	v_cndmask_b32_e64 v17, v93, v47, s[0:1]
	v_cndmask_b32_e64 v41, v91, v45, s[0:1]
	v_fmac_f32_e32 v41, v17, v3
	v_mul_f32_e32 v17, v17, v0
	v_fmac_f32_e32 v18, v32, v2
	v_mul_f32_e32 v32, v1, v32
	v_fmac_f32_e32 v31, v33, v2
	v_mul_f32_e32 v33, v1, v33
	v_fmac_f32_e32 v30, v34, v2
	v_mul_f32_e32 v34, v1, v34
	v_fmac_f32_e32 v29, v35, v2
	v_mul_f32_e32 v1, v1, v35
	v_fmac_f32_e32 v27, v37, v13
	v_mul_f32_e32 v35, v37, v10
	v_fmac_f32_e32 v24, v40, v15
	v_mul_f32_e32 v37, v40, v14
	v_fmac_f32_e32 v9, v4, v41
	v_mul_f32_e32 v40, v4, v17
	v_cvt_pk_bf16_f32 v4, v18, v32
	v_fmac_f32_e32 v19, v20, v13
	v_mul_f32_e32 v2, v20, v10
	v_fmac_f32_e32 v28, v36, v13
	v_mul_f32_e32 v20, v36, v10
	v_fmac_f32_e32 v26, v38, v13
	v_mul_f32_e32 v10, v38, v10
	v_fmac_f32_e32 v23, v12, v15
	v_mul_f32_e32 v38, v12, v14
	global_load_dword v172, v[130:131], off offset:256
	global_load_dword v173, v[126:127], off offset:256
	global_load_dword v174, v[128:129], off offset:256
	global_store_dword v96, v4, s[100:101] offset:128 nt
	v_fmac_f32_e32 v21, v22, v15
	v_mul_f32_e32 v22, v22, v14
	v_fmac_f32_e32 v25, v39, v15
	v_mul_f32_e32 v36, v39, v14
	v_cvt_pk_bf16_f32 v4, v31, v33
	global_store_dword v88, v4, s[100:101] offset:128 nt
	v_cvt_pk_bf16_f32 v4, v30, v34
	global_store_dword v98, v4, s[100:101] offset:128 nt
	v_cvt_pk_bf16_f32 v1, v29, v1
	global_store_dword v100, v1, s[100:101] offset:128 nt
	v_cvt_pk_bf16_f32 v1, v19, v2
	global_store_dword v102, v1, s[100:101] offset:128 nt
	v_cvt_pk_bf16_f32 v1, v28, v20
	global_store_dword v104, v1, s[100:101] offset:128 nt
	v_cvt_pk_bf16_f32 v1, v27, v35
	global_store_dword v106, v1, s[100:101] offset:128 nt
	v_cvt_pk_bf16_f32 v1, v26, v10
	global_store_dword v108, v1, s[100:101] offset:128 nt
	v_cvt_pk_bf16_f32 v1, v21, v22
	global_store_dword v110, v1, s[100:101] offset:128 nt
	v_cvt_pk_bf16_f32 v1, v25, v36
	global_store_dword v112, v1, s[100:101] offset:128 nt
	v_cvt_pk_bf16_f32 v1, v24, v37
	global_store_dword v114, v1, s[100:101] offset:128 nt
	v_fmac_f32_e32 v6, v16, v41
	v_mul_f32_e32 v16, v16, v17
	v_cvt_pk_bf16_f32 v1, v23, v38
	global_store_dword v116, v1, s[100:101] offset:128 nt
	v_fmac_f32_e32 v5, v7, v41
	v_mul_f32_e32 v39, v7, v17
	v_cvt_pk_bf16_f32 v1, v6, v16
	global_store_dword v118, v1, s[100:101] offset:128 nt
	v_cvt_pk_bf16_f32 v1, v5, v39
	v_fmac_f32_e32 v11, v8, v41
	v_mul_f32_e32 v8, v8, v17
	global_store_dword v120, v1, s[100:101] offset:128 nt
	v_cvt_pk_bf16_f32 v1, v9, v40
	global_store_dword v122, v1, s[100:101] offset:128 nt
	v_cvt_pk_bf16_f32 v2, v11, v8
	global_store_dword v124, v2, s[100:101] offset:128 nt
	s_and_saveexec_b64 s[8:9], s[4:5]
	s_cbranch_execz .LBB0_346
	v_add_u32_e32 v12, 0x800, v142
	ds_read2_b64 v[0:3], v12 offset1:32
	ds_read2_b64 v[4:7], v12 offset0:64 offset1:96
	ds_read2_b64 v[8:11], v12 offset0:128 offset1:160
	ds_read2_b64 v[12:15], v12 offset0:192 offset1:224
	s_waitcnt lgkmcnt(3)
	v_fma_f32 v16, 0, v0, v1
	v_pk_mul_f32 v[0:1], v[0:1], v[2:3]
	v_fma_f32 v2, v2, v16, v3
	s_waitcnt lgkmcnt(2)
	v_fma_f32 v2, v4, v2, v5
	v_fma_f32 v2, v6, v2, v7
	s_waitcnt lgkmcnt(1)
	v_fma_f32 v3, v8, v2, v9
	v_mov_b32_e32 v2, v0
	v_mov_b32_e32 v16, v4
	v_mov_b32_e32 v17, v10
	v_pk_mul_f32 v[0:1], v[0:1], v[4:5]
	v_pk_fma_f32 v[2:3], v[2:3], v[16:17], v[10:11]
	v_pk_mul_f32 v[0:1], v[0:1], v[6:7]
	s_waitcnt lgkmcnt(0)
	v_mov_b32_e32 v9, v12
	v_mov_b32_e32 v1, v3
	v_pk_mul_f32 v[2:3], v[0:1], v[8:9]
	v_pk_fma_f32 v[0:1], v[0:1], v[8:9], v[12:13]
	v_pk_mul_f32 v[2:3], v[2:3], v[10:11]
	v_mov_b32_e32 v4, v12
	v_mov_b32_e32 v0, v2
	v_mov_b32_e32 v5, v14
	v_pk_mul_f32 v[2:3], v[2:3], v[12:13]
	v_pk_fma_f32 v[0:1], v[0:1], v[4:5], v[14:15]
	v_pk_mul_f32 v[2:3], v[2:3], v[14:15]
	v_add_u32_e32 v0, 32, v92
	v_mov_b32_e32 v3, v1
	v_ashrrev_i32_e32 v1, 31, v0
	v_lshl_add_u64 v[0:1], v[0:1], 3, s[24:25]
	global_store_dwordx2 v[0:1], v[2:3], off

.LBB0_357:
	v_cndmask_b32_e64 v1, v13, 1.0, s[0:1]
	v_cndmask_b32_e64 v2, v10, 0, s[0:1]
	v_fmac_f32_e32 v2, v1, v3
	v_mul_f32_e32 v1, v1, v0
	v_cndmask_b32_e64 v10, v42, v15, s[0:1]
	v_cndmask_b32_e64 v13, v17, v14, s[0:1]
	v_fmac_f32_e32 v13, v10, v3
	v_mul_f32_e32 v10, v10, v0
	v_cndmask_b32_e64 v14, v46, v43, s[0:1]
	v_cndmask_b32_e64 v15, v44, v41, s[0:1]
	v_fmac_f32_e32 v15, v14, v3
	v_mul_f32_e32 v14, v14, v0
	v_cndmask_b32_e64 v17, v93, v47, s[0:1]
	v_cndmask_b32_e64 v41, v91, v45, s[0:1]
	v_fmac_f32_e32 v41, v17, v3
	v_mul_f32_e32 v17, v17, v0
	v_fmac_f32_e32 v18, v32, v2
	v_mul_f32_e32 v32, v1, v32
	v_fmac_f32_e32 v31, v33, v2
	v_mul_f32_e32 v33, v1, v33
	v_fmac_f32_e32 v30, v34, v2
	v_mul_f32_e32 v34, v1, v34
	v_fmac_f32_e32 v29, v35, v2
	v_mul_f32_e32 v1, v1, v35
	v_fmac_f32_e32 v27, v37, v13
	v_mul_f32_e32 v35, v37, v10
	v_fmac_f32_e32 v24, v40, v15
	v_mul_f32_e32 v37, v40, v14
	v_fmac_f32_e32 v9, v4, v41
	v_mul_f32_e32 v40, v4, v17
	v_cvt_pk_bf16_f32 v4, v18, v32
	v_fmac_f32_e32 v19, v20, v13
	v_mul_f32_e32 v2, v20, v10
	v_fmac_f32_e32 v28, v36, v13
	v_mul_f32_e32 v20, v36, v10
	v_fmac_f32_e32 v26, v38, v13
	v_mul_f32_e32 v10, v38, v10
	v_fmac_f32_e32 v23, v12, v15
	v_mul_f32_e32 v38, v12, v14
	global_load_dword v172, v[130:131], off offset:384
	global_load_dword v173, v[126:127], off offset:384
	global_load_dword v174, v[128:129], off offset:384
	global_store_dword v96, v4, s[100:101] offset:256 nt
	v_fmac_f32_e32 v21, v22, v15
	v_mul_f32_e32 v22, v22, v14
	v_fmac_f32_e32 v25, v39, v15
	v_mul_f32_e32 v36, v39, v14
	v_cvt_pk_bf16_f32 v4, v31, v33
	global_store_dword v88, v4, s[100:101] offset:256 nt
	v_cvt_pk_bf16_f32 v4, v30, v34
	global_store_dword v98, v4, s[100:101] offset:256 nt
	v_cvt_pk_bf16_f32 v1, v29, v1
	global_store_dword v100, v1, s[100:101] offset:256 nt
	v_cvt_pk_bf16_f32 v1, v19, v2
	global_store_dword v102, v1, s[100:101] offset:256 nt
	v_cvt_pk_bf16_f32 v1, v28, v20
	global_store_dword v104, v1, s[100:101] offset:256 nt
	v_cvt_pk_bf16_f32 v1, v27, v35
	global_store_dword v106, v1, s[100:101] offset:256 nt
	v_cvt_pk_bf16_f32 v1, v26, v10
	global_store_dword v108, v1, s[100:101] offset:256 nt
	v_cvt_pk_bf16_f32 v1, v21, v22
	global_store_dword v110, v1, s[100:101] offset:256 nt
	v_cvt_pk_bf16_f32 v1, v25, v36
	global_store_dword v112, v1, s[100:101] offset:256 nt
	v_cvt_pk_bf16_f32 v1, v24, v37
	global_store_dword v114, v1, s[100:101] offset:256 nt
	v_fmac_f32_e32 v6, v16, v41
	v_mul_f32_e32 v16, v16, v17
	v_cvt_pk_bf16_f32 v1, v23, v38
	global_store_dword v116, v1, s[100:101] offset:256 nt
	v_fmac_f32_e32 v5, v7, v41
	v_mul_f32_e32 v39, v7, v17
	v_cvt_pk_bf16_f32 v1, v6, v16
	global_store_dword v118, v1, s[100:101] offset:256 nt
	v_cvt_pk_bf16_f32 v1, v5, v39
	v_fmac_f32_e32 v11, v8, v41
	v_mul_f32_e32 v8, v8, v17
	global_store_dword v120, v1, s[100:101] offset:256 nt
	v_cvt_pk_bf16_f32 v1, v9, v40
	global_store_dword v122, v1, s[100:101] offset:256 nt
	v_cvt_pk_bf16_f32 v2, v11, v8
	global_store_dword v124, v2, s[100:101] offset:256 nt
	s_and_saveexec_b64 s[8:9], s[4:5]
	s_cbranch_execz .LBB0_359
	v_add_u32_e32 v12, 0x1000, v142
	ds_read2_b64 v[0:3], v12 offset1:32
	ds_read2_b64 v[4:7], v12 offset0:64 offset1:96
	ds_read2_b64 v[8:11], v12 offset0:128 offset1:160
	ds_read2_b64 v[12:15], v12 offset0:192 offset1:224
	s_waitcnt lgkmcnt(3)
	v_fma_f32 v16, 0, v0, v1
	v_pk_mul_f32 v[0:1], v[0:1], v[2:3]
	v_fma_f32 v2, v2, v16, v3
	s_waitcnt lgkmcnt(2)
	v_fma_f32 v2, v4, v2, v5
	v_fma_f32 v2, v6, v2, v7
	s_waitcnt lgkmcnt(1)
	v_fma_f32 v3, v8, v2, v9
	v_mov_b32_e32 v2, v0
	v_mov_b32_e32 v16, v4
	v_mov_b32_e32 v17, v10
	v_pk_mul_f32 v[0:1], v[0:1], v[4:5]
	v_pk_fma_f32 v[2:3], v[2:3], v[16:17], v[10:11]
	v_pk_mul_f32 v[0:1], v[0:1], v[6:7]
	s_waitcnt lgkmcnt(0)
	v_mov_b32_e32 v9, v12
	v_mov_b32_e32 v1, v3
	v_pk_mul_f32 v[2:3], v[0:1], v[8:9]
	v_pk_fma_f32 v[0:1], v[0:1], v[8:9], v[12:13]
	v_pk_mul_f32 v[2:3], v[2:3], v[10:11]
	v_mov_b32_e32 v4, v12
	v_mov_b32_e32 v0, v2
	v_mov_b32_e32 v5, v14
	v_pk_mul_f32 v[2:3], v[2:3], v[12:13]
	v_pk_fma_f32 v[0:1], v[0:1], v[4:5], v[14:15]
	v_pk_mul_f32 v[2:3], v[2:3], v[14:15]
	v_add_u32_e32 v0, 64, v92
	v_mov_b32_e32 v3, v1
	v_ashrrev_i32_e32 v1, 31, v0
	v_lshl_add_u64 v[0:1], v[0:1], 3, s[24:25]
	global_store_dwordx2 v[0:1], v[2:3], off

.LBB0_370:
	v_cndmask_b32_e64 v1, v13, 1.0, s[0:1]
	v_cndmask_b32_e64 v2, v10, 0, s[0:1]
	v_fmac_f32_e32 v2, v1, v3
	v_mul_f32_e32 v1, v1, v0
	v_cndmask_b32_e64 v10, v42, v15, s[0:1]
	v_cndmask_b32_e64 v13, v17, v14, s[0:1]
	v_fmac_f32_e32 v13, v10, v3
	v_mul_f32_e32 v10, v10, v0
	v_cndmask_b32_e64 v14, v46, v43, s[0:1]
	v_cndmask_b32_e64 v15, v44, v41, s[0:1]
	v_fmac_f32_e32 v15, v14, v3
	v_mul_f32_e32 v14, v14, v0
	v_cndmask_b32_e64 v17, v49, v47, s[0:1]
	v_cndmask_b32_e64 v41, v48, v45, s[0:1]
	v_fmac_f32_e32 v41, v17, v3
	v_mul_f32_e32 v17, v17, v0
	v_fmac_f32_e32 v18, v32, v2
	v_mul_f32_e32 v32, v1, v32
	v_fmac_f32_e32 v31, v33, v2
	v_mul_f32_e32 v33, v1, v33
	v_fmac_f32_e32 v30, v34, v2
	v_mul_f32_e32 v34, v1, v34
	v_fmac_f32_e32 v29, v35, v2
	v_mul_f32_e32 v1, v1, v35
	v_fmac_f32_e32 v27, v37, v13
	v_mul_f32_e32 v35, v37, v10
	v_fmac_f32_e32 v24, v40, v15
	v_mul_f32_e32 v37, v40, v14
	v_fmac_f32_e32 v9, v4, v41
	v_mul_f32_e32 v40, v4, v17
	v_cvt_pk_bf16_f32 v4, v18, v32
	v_fmac_f32_e32 v19, v20, v13
	v_mul_f32_e32 v2, v20, v10
	v_fmac_f32_e32 v28, v36, v13
	v_mul_f32_e32 v20, v36, v10
	v_fmac_f32_e32 v26, v38, v13
	v_mul_f32_e32 v10, v38, v10
	v_fmac_f32_e32 v23, v12, v15
	v_mul_f32_e32 v38, v12, v14
	global_store_dword v96, v4, s[100:101] offset:384 nt
	v_fmac_f32_e32 v21, v22, v15
	v_mul_f32_e32 v22, v22, v14
	v_fmac_f32_e32 v25, v39, v15
	v_mul_f32_e32 v36, v39, v14
	v_cvt_pk_bf16_f32 v4, v31, v33
	global_store_dword v88, v4, s[100:101] offset:384 nt
	v_cvt_pk_bf16_f32 v4, v30, v34
	global_store_dword v98, v4, s[100:101] offset:384 nt
	v_cvt_pk_bf16_f32 v1, v29, v1
	global_store_dword v100, v1, s[100:101] offset:384 nt
	v_cvt_pk_bf16_f32 v1, v19, v2
	global_store_dword v102, v1, s[100:101] offset:384 nt
	v_cvt_pk_bf16_f32 v1, v28, v20
	global_store_dword v104, v1, s[100:101] offset:384 nt
	v_cvt_pk_bf16_f32 v1, v27, v35
	global_store_dword v106, v1, s[100:101] offset:384 nt
	v_cvt_pk_bf16_f32 v1, v26, v10
	global_store_dword v108, v1, s[100:101] offset:384 nt
	v_cvt_pk_bf16_f32 v1, v21, v22
	global_store_dword v110, v1, s[100:101] offset:384 nt
	v_cvt_pk_bf16_f32 v1, v25, v36
	global_store_dword v112, v1, s[100:101] offset:384 nt
	v_cvt_pk_bf16_f32 v1, v24, v37
	global_store_dword v114, v1, s[100:101] offset:384 nt
	v_fmac_f32_e32 v6, v16, v41
	v_mul_f32_e32 v16, v16, v17
	v_cvt_pk_bf16_f32 v1, v23, v38
	global_store_dword v116, v1, s[100:101] offset:384 nt
	v_fmac_f32_e32 v5, v7, v41
	v_mul_f32_e32 v39, v7, v17
	v_cvt_pk_bf16_f32 v1, v6, v16
	global_store_dword v118, v1, s[100:101] offset:384 nt
	v_cvt_pk_bf16_f32 v1, v5, v39
	v_fmac_f32_e32 v11, v8, v41
	v_mul_f32_e32 v8, v8, v17
	global_store_dword v120, v1, s[100:101] offset:384 nt
	v_cvt_pk_bf16_f32 v1, v9, v40
	global_store_dword v122, v1, s[100:101] offset:384 nt
	v_cvt_pk_bf16_f32 v2, v11, v8
	global_store_dword v124, v2, s[100:101] offset:384 nt
	s_and_saveexec_b64 s[0:1], s[4:5]
	s_cbranch_execz .LBB0_300
	v_add_u32_e32 v12, 0x1800, v142
	ds_read2_b64 v[0:3], v12 offset1:32
	ds_read2_b64 v[4:7], v12 offset0:64 offset1:96
	ds_read2_b64 v[8:11], v12 offset0:128 offset1:160
	ds_read2_b64 v[12:15], v12 offset0:192 offset1:224
	s_waitcnt lgkmcnt(3)
	v_fma_f32 v16, 0, v0, v1
	v_pk_mul_f32 v[0:1], v[0:1], v[2:3]
	v_fma_f32 v2, v2, v16, v3
	s_waitcnt lgkmcnt(2)
	v_fma_f32 v2, v4, v2, v5
	v_fma_f32 v2, v6, v2, v7
	s_waitcnt lgkmcnt(1)
	v_fma_f32 v3, v8, v2, v9
	v_mov_b32_e32 v2, v0
	v_mov_b32_e32 v16, v4
	v_mov_b32_e32 v17, v10
	v_pk_mul_f32 v[0:1], v[0:1], v[4:5]
	v_pk_fma_f32 v[2:3], v[2:3], v[16:17], v[10:11]
	v_pk_mul_f32 v[0:1], v[0:1], v[6:7]
	s_waitcnt lgkmcnt(0)
	v_mov_b32_e32 v9, v12
	v_mov_b32_e32 v1, v3
	v_pk_mul_f32 v[2:3], v[0:1], v[8:9]
	v_pk_fma_f32 v[0:1], v[0:1], v[8:9], v[12:13]
	v_pk_mul_f32 v[2:3], v[2:3], v[10:11]
	v_mov_b32_e32 v4, v12
	v_mov_b32_e32 v0, v2
	v_mov_b32_e32 v5, v14
	v_pk_mul_f32 v[2:3], v[2:3], v[12:13]
	v_pk_fma_f32 v[0:1], v[0:1], v[4:5], v[14:15]
	v_pk_mul_f32 v[2:3], v[2:3], v[14:15]
	v_add_u32_e32 v0, 0x60, v92
	v_mov_b32_e32 v3, v1
	v_ashrrev_i32_e32 v1, 31, v0
	v_lshl_add_u64 v[0:1], v[0:1], 3, s[24:25]
	global_store_dwordx2 v[0:1], v[2:3], off
	s_branch .LBB0_300
